# diff loop: the 8 V-fragment reads for the post-barrier PV group moved from the QK-side read burst to the bare PV MFMAs before the barrier (LDS traffic evened out over the tile)
# baseline (speedup 1.0000x reference)
.LBB0_366:
	s_min_u32 s26, s24, 28
	s_mul_i32 s26, s26, 0x48000
	s_add_i32 s27, s17, s23
	s_add_i32 s58, s26, 0xd8000
	s_waitcnt vmcnt(4)
	s_barrier
	s_add_i32 s26, s22, 0
	v_add_u32_e32 v118, s26, v197
	v_add_u32_e32 v122, s26, v198
	v_add_u32_e32 v126, s26, v199
	ds_read_b128 v[114:117], v118 offset:0
	ds_read_b128 v[182:185], v118 offset:4096
	ds_read_b128 v[118:121], v122 offset:0
	ds_read_b128 v[178:181], v122 offset:4096
	ds_read_b128 v[122:125], v126 offset:0
	ds_read_b128 v[166:169], v126 offset:4096
	v_add_u32_e32 v225, s26, v200
	ds_read_b128 v[126:129], v225 offset:0
	ds_read_b128 v[146:149], v225 offset:4096
	s_add_i32 s25, s25, 0
	s_setprio 1
	s_waitcnt lgkmcnt(8)
	v_mfma_f32_32x32x16_bf16 v[66:81], v[246:249], v[170:173], v[66:81]
	v_exp_f32_e32 v232, v88
	v_exp_f32_e32 v233, v89
	v_exp_f32_e32 v234, v90
	v_mfma_f32_32x32x16_bf16 v[50:65], v[202:205], v[170:173], v[50:65]
	v_exp_f32_e32 v235, v91
	v_exp_f32_e32 v236, v92
	v_exp_f32_e32 v237, v93
	v_mfma_f32_32x32x16_bf16 v[34:49], v[210:213], v[170:173], v[34:49]
	v_add_u32_e32 v210, s25, v201
	v_add_u32_e32 v211, s25, v206
	v_exp_f32_e32 v238, v94
	v_exp_f32_e32 v239, v95
	v_mfma_f32_32x32x16_bf16 v[18:33], v[216:219], v[170:173], v[18:33]
	v_exp_f32_e32 v240, v96
	v_exp_f32_e32 v241, v97
	v_cvt_pk_bf16_f32 v170, v226, v227
	v_cvt_pk_bf16_f32 v171, v228, v229
	v_cvt_pk_bf16_f32 v172, v230, v231
	v_cvt_pk_bf16_f32 v173, v232, v233
	v_cvt_pk_bf16_f32 v174, v234, v235
	v_cvt_pk_bf16_f32 v175, v236, v237
	v_cvt_pk_bf16_f32 v176, v238, v239
	v_cvt_pk_bf16_f32 v177, v240, v241
	s_waitcnt lgkmcnt(7)
	v_mfma_f32_32x32x16_bf16 v[82:97], v[114:117], v[130:133], v[2:17]
	v_add_f32_e32 v114, 0, v226
	v_add_f32_e32 v114, v227, v114
	v_add_f32_e32 v114, v228, v114
	v_add_f32_e32 v114, v229, v114
	v_add_f32_e32 v114, v230, v114
	v_add_f32_e32 v114, v231, v114
	v_add_f32_e32 v114, v232, v114
	s_waitcnt lgkmcnt(5)
	v_mfma_f32_32x32x16_bf16 v[82:97], v[118:121], v[134:137], v[82:97]
	v_add_f32_e32 v114, v233, v114
	v_add_f32_e32 v114, v234, v114
	v_add_f32_e32 v114, v235, v114
	v_add_f32_e32 v114, v236, v114
	v_add_f32_e32 v114, v237, v114
	v_add_f32_e32 v114, v238, v114
	v_add_f32_e32 v114, v239, v114
	v_lshl_add_u64 v[242:243], v[186:187], 0, s[58:59]
	s_mov_b32 m0, s27
	s_nop 0
	global_load_lds_dwordx4 v[242:243], off
	s_waitcnt lgkmcnt(3)
	v_mfma_f32_32x32x16_bf16 v[82:97], v[122:125], v[138:141], v[82:97]
	v_add_f32_e32 v114, v240, v114
	v_add_f32_e32 v225, v241, v114
	v_lshl_add_u64 v[242:243], v[242:243], 0, s[28:29]
	s_add_i32 m0, s27, 0x2000
	s_nop 0
	global_load_lds_dwordx4 v[242:243], off
	s_waitcnt lgkmcnt(1)
	v_mfma_f32_32x32x16_bf16 v[82:97], v[126:129], v[142:145], v[82:97]
	v_lshl_add_u64 v[242:243], v[188:189], 0, s[58:59]
	s_add_i32 m0, s27, 0x4000
	s_nop 0
	global_load_lds_dwordx4 v[242:243], off
	v_mfma_f32_32x32x16_bf16 v[114:129], v[182:185], v[130:133], v[2:17]
	v_lshl_add_u64 v[242:243], v[242:243], 0, s[34:35]
	s_add_i32 m0, s27, 0x6000
	s_nop 0
	global_load_lds_dwordx4 v[242:243], off
	v_mfma_f32_32x32x16_bf16 v[114:129], v[178:181], v[134:137], v[114:129]
	v_mfma_f32_32x32x16_bf16 v[114:129], v[166:169], v[138:141], v[114:129]
	s_setprio 0
	ds_read_b64_tr_b16 v[166:167], v210 offset:4096
	ds_read_b64_tr_b16 v[168:169], v210 offset:6144
	ds_read_b64_tr_b16 v[178:179], v211 offset:4096
	ds_read_b64_tr_b16 v[180:181], v211 offset:6144
	ds_read_b64_tr_b16 v[182:183], v223 offset:4096
	ds_read_b64_tr_b16 v[184:185], v223 offset:6144
	ds_read_b64_tr_b16 v[226:227], v224 offset:4096
	ds_read_b64_tr_b16 v[228:229], v224 offset:6144
	ds_read_b64_tr_b16 v[230:231], v210 offset:8192
	ds_read_b64_tr_b16 v[232:233], v210 offset:10240
	ds_read_b64_tr_b16 v[234:235], v211 offset:8192
	ds_read_b64_tr_b16 v[236:237], v211 offset:10240
	ds_read_b64_tr_b16 v[238:239], v223 offset:8192
	ds_read_b64_tr_b16 v[240:241], v223 offset:10240
	ds_read_b64_tr_b16 v[242:243], v224 offset:8192
	ds_read_b64_tr_b16 v[244:245], v224 offset:10240
	s_waitcnt lgkmcnt(15)
	s_setprio 1
	v_mfma_f32_32x32x16_bf16 v[66:81], v[162:165], v[170:173], v[66:81]
	v_exp_f32_e32 v162, v98
	v_exp_f32_e32 v163, v99
	s_nop 0
	v_cvt_pk_bf16_f32 v98, v162, v163
	v_mfma_f32_32x32x16_bf16 v[50:65], v[158:161], v[170:173], v[50:65]
	v_exp_f32_e32 v158, v100
	v_exp_f32_e32 v159, v101
	s_nop 0
	v_cvt_pk_bf16_f32 v99, v158, v159
	v_mfma_f32_32x32x16_bf16 v[34:49], v[154:157], v[170:173], v[34:49]
	v_exp_f32_e32 v154, v102
	v_exp_f32_e32 v155, v103
	s_nop 0
	v_cvt_pk_bf16_f32 v100, v154, v155
	v_mfma_f32_32x32x16_bf16 v[18:33], v[150:153], v[170:173], v[18:33]
	v_exp_f32_e32 v150, v104
	v_exp_f32_e32 v151, v105
	v_add_f32_e32 v152, v162, v225
	v_add_f32_e32 v152, v163, v152
	v_add_f32_e32 v152, v158, v152
	v_cvt_pk_bf16_f32 v101, v150, v151
	v_add_f32_e32 v152, v159, v152
	s_waitcnt lgkmcnt(14)
	v_mfma_f32_32x32x16_bf16 v[66:81], v[166:169], v[174:177], v[66:81]
	v_exp_f32_e32 v106, v106
	v_exp_f32_e32 v107, v107
	v_add_f32_e32 v152, v154, v152
	v_add_f32_e32 v152, v155, v152
	v_add_f32_e32 v150, v150, v152
	v_cvt_pk_bf16_f32 v170, v106, v107
	v_add_f32_e32 v150, v151, v150
	s_waitcnt lgkmcnt(12)
	v_mfma_f32_32x32x16_bf16 v[50:65], v[178:181], v[174:177], v[50:65]
	v_exp_f32_e32 v108, v108
	v_exp_f32_e32 v109, v109
	v_add_f32_e32 v106, v106, v150
	v_add_f32_e32 v106, v107, v106
	v_add_f32_e32 v106, v108, v106
	v_cvt_pk_bf16_f32 v171, v108, v109
	v_add_f32_e32 v106, v109, v106
	s_waitcnt lgkmcnt(10)
	v_mfma_f32_32x32x16_bf16 v[34:49], v[182:185], v[174:177], v[34:49]
	v_exp_f32_e32 v110, v110
	v_exp_f32_e32 v111, v111
	v_add_f32_e32 v106, v110, v106
	v_cvt_pk_bf16_f32 v172, v110, v111
	v_add_f32_e32 v106, v111, v106
	s_waitcnt lgkmcnt(8)
	v_mfma_f32_32x32x16_bf16 v[18:33], v[226:229], v[174:177], v[18:33]
	v_exp_f32_e32 v112, v112
	v_exp_f32_e32 v113, v113
	v_add_f32_e32 v106, v112, v106
	v_cvt_pk_bf16_f32 v173, v112, v113
	v_add_f32_e32 v106, v113, v106
	v_mfma_f32_32x32x16_bf16 v[114:129], v[146:149], v[142:145], v[114:129]
	s_waitcnt lgkmcnt(0)
	v_mfma_f32_32x32x16_bf16 v[66:81], v[230:233], v[98:101], v[66:81]
	v_add_f32_e32 v209, v209, v106
	ds_read_b64_tr_b16 v[246:247], v210 offset:12288
	ds_read_b64_tr_b16 v[248:249], v210 offset:14336
	ds_read_b64_tr_b16 v[202:203], v211 offset:12288
	ds_read_b64_tr_b16 v[204:205], v211 offset:14336
	ds_read_b64_tr_b16 v[216:217], v224 offset:12288
	ds_read_b64_tr_b16 v[218:219], v224 offset:14336
	ds_read_b64_tr_b16 v[210:211], v223 offset:12288
	ds_read_b64_tr_b16 v[212:213], v223 offset:14336
	v_add_u32_e32 v106, s22, v201
	v_add_u32_e32 v107, s22, v206
	ds_read_b64_tr_b16 v[162:163], v106 offset:0
	ds_read_b64_tr_b16 v[164:165], v106 offset:2048
	ds_read_b64_tr_b16 v[158:159], v107 offset:0
	ds_read_b64_tr_b16 v[160:161], v107 offset:2048
	v_mfma_f32_32x32x16_bf16 v[50:65], v[234:237], v[98:101], v[50:65]
	v_exp_f32_e32 v226, v82
	v_exp_f32_e32 v227, v83
	v_exp_f32_e32 v228, v84
	v_mfma_f32_32x32x16_bf16 v[34:49], v[238:241], v[98:101], v[34:49]
	v_add_u32_e32 v223, s22, v207
	v_add_u32_e32 v224, s22, v208
	ds_read_b64_tr_b16 v[154:155], v223 offset:0
	ds_read_b64_tr_b16 v[156:157], v223 offset:2048
	ds_read_b64_tr_b16 v[150:151], v224 offset:0
	ds_read_b64_tr_b16 v[152:153], v224 offset:2048
	v_mfma_f32_32x32x16_bf16 v[18:33], v[242:245], v[98:101], v[18:33]
	v_exp_f32_e32 v229, v85
	v_exp_f32_e32 v230, v86
	v_exp_f32_e32 v231, v87
	s_setprio 0
	s_add_i32 s26, s22, 0x8000
	s_cmp_lg_u32 s22, 0x18000
	s_mov_b32 s25, s22
	s_cselect_b32 s22, s26, 0
	s_add_i32 s26, s23, 0x8000
	s_cmp_lg_u32 s23, 0x18000
	s_cselect_b32 s23, s26, 0
	s_add_i32 s24, s24, 1
	s_min_u32 s26, s24, 28
	s_mul_i32 s26, s26, 0x48000
	s_add_i32 s27, s17, s23
	s_add_i32 s58, s26, 0xd8000
	s_waitcnt vmcnt(4)
	s_barrier
	s_add_i32 s26, s22, 0
	v_add_u32_e32 v102, s26, v197
	v_add_u32_e32 v106, s26, v198
	v_add_u32_e32 v110, s26, v199
	ds_read_b128 v[98:101], v102 offset:0
	ds_read_b128 v[182:185], v102 offset:4096
	ds_read_b128 v[102:105], v106 offset:0
	ds_read_b128 v[178:181], v106 offset:4096
	ds_read_b128 v[106:109], v110 offset:0
	ds_read_b128 v[166:169], v110 offset:4096
	v_add_u32_e32 v225, s26, v200
	ds_read_b128 v[110:113], v225 offset:0
	ds_read_b128 v[146:149], v225 offset:4096
	s_add_i32 s25, s25, 0
	s_setprio 1
	s_waitcnt lgkmcnt(8)
	v_mfma_f32_32x32x16_bf16 v[66:81], v[246:249], v[170:173], v[66:81]
	v_exp_f32_e32 v232, v88
	v_exp_f32_e32 v233, v89
	v_exp_f32_e32 v234, v90
	v_mfma_f32_32x32x16_bf16 v[50:65], v[202:205], v[170:173], v[50:65]
	v_exp_f32_e32 v235, v91
	v_exp_f32_e32 v236, v92
	v_exp_f32_e32 v237, v93
	v_mfma_f32_32x32x16_bf16 v[34:49], v[210:213], v[170:173], v[34:49]
	v_add_u32_e32 v210, s25, v201
	v_add_u32_e32 v211, s25, v206
	v_exp_f32_e32 v238, v94
	v_exp_f32_e32 v239, v95
	v_mfma_f32_32x32x16_bf16 v[18:33], v[216:219], v[170:173], v[18:33]
	v_exp_f32_e32 v240, v96
	v_exp_f32_e32 v241, v97
	v_cvt_pk_bf16_f32 v170, v226, v227
	v_cvt_pk_bf16_f32 v171, v228, v229
	v_cvt_pk_bf16_f32 v172, v230, v231
	v_cvt_pk_bf16_f32 v173, v232, v233
	v_cvt_pk_bf16_f32 v174, v234, v235
	v_cvt_pk_bf16_f32 v175, v236, v237
	v_cvt_pk_bf16_f32 v176, v238, v239
	v_cvt_pk_bf16_f32 v177, v240, v241
	s_waitcnt lgkmcnt(7)
	v_mfma_f32_32x32x16_bf16 v[82:97], v[98:101], v[130:133], v[2:17]
	v_add_f32_e32 v98, 0, v226
	v_add_f32_e32 v98, v227, v98
	v_add_f32_e32 v98, v228, v98
	v_add_f32_e32 v98, v229, v98
	v_add_f32_e32 v98, v230, v98
	v_add_f32_e32 v98, v231, v98
	v_add_f32_e32 v98, v232, v98
	s_waitcnt lgkmcnt(5)
	v_mfma_f32_32x32x16_bf16 v[82:97], v[102:105], v[134:137], v[82:97]
	v_add_f32_e32 v98, v233, v98
	v_add_f32_e32 v98, v234, v98
	v_add_f32_e32 v98, v235, v98
	v_add_f32_e32 v98, v236, v98
	v_add_f32_e32 v98, v237, v98
	v_add_f32_e32 v98, v238, v98
	v_add_f32_e32 v98, v239, v98
	v_lshl_add_u64 v[242:243], v[186:187], 0, s[58:59]
	s_mov_b32 m0, s27
	s_nop 0
	global_load_lds_dwordx4 v[242:243], off
	s_waitcnt lgkmcnt(3)
	v_mfma_f32_32x32x16_bf16 v[82:97], v[106:109], v[138:141], v[82:97]
	v_add_f32_e32 v98, v240, v98
	v_add_f32_e32 v225, v241, v98
	v_lshl_add_u64 v[242:243], v[242:243], 0, s[28:29]
	s_add_i32 m0, s27, 0x2000
	s_nop 0
	global_load_lds_dwordx4 v[242:243], off
	s_waitcnt lgkmcnt(1)
	v_mfma_f32_32x32x16_bf16 v[82:97], v[110:113], v[142:145], v[82:97]
	v_lshl_add_u64 v[242:243], v[188:189], 0, s[58:59]
	s_add_i32 m0, s27, 0x4000
	s_nop 0
	global_load_lds_dwordx4 v[242:243], off
	v_mfma_f32_32x32x16_bf16 v[98:113], v[182:185], v[130:133], v[2:17]
	v_lshl_add_u64 v[242:243], v[242:243], 0, s[34:35]
	s_add_i32 m0, s27, 0x6000
	s_nop 0
	global_load_lds_dwordx4 v[242:243], off
	v_mfma_f32_32x32x16_bf16 v[98:113], v[178:181], v[134:137], v[98:113]
	v_mfma_f32_32x32x16_bf16 v[98:113], v[166:169], v[138:141], v[98:113]
	s_setprio 0
	ds_read_b64_tr_b16 v[166:167], v210 offset:4096
	ds_read_b64_tr_b16 v[168:169], v210 offset:6144
	ds_read_b64_tr_b16 v[178:179], v211 offset:4096
	ds_read_b64_tr_b16 v[180:181], v211 offset:6144
	ds_read_b64_tr_b16 v[182:183], v223 offset:4096
	ds_read_b64_tr_b16 v[184:185], v223 offset:6144
	ds_read_b64_tr_b16 v[226:227], v224 offset:4096
	ds_read_b64_tr_b16 v[228:229], v224 offset:6144
	ds_read_b64_tr_b16 v[230:231], v210 offset:8192
	ds_read_b64_tr_b16 v[232:233], v210 offset:10240
	ds_read_b64_tr_b16 v[234:235], v211 offset:8192
	ds_read_b64_tr_b16 v[236:237], v211 offset:10240
	ds_read_b64_tr_b16 v[238:239], v223 offset:8192
	ds_read_b64_tr_b16 v[240:241], v223 offset:10240
	ds_read_b64_tr_b16 v[242:243], v224 offset:8192
	ds_read_b64_tr_b16 v[244:245], v224 offset:10240
	s_waitcnt lgkmcnt(15)
	s_setprio 1
	v_mfma_f32_32x32x16_bf16 v[66:81], v[162:165], v[170:173], v[66:81]
	v_exp_f32_e32 v162, v114
	v_exp_f32_e32 v163, v115
	s_nop 0
	v_cvt_pk_bf16_f32 v114, v162, v163
	v_mfma_f32_32x32x16_bf16 v[50:65], v[158:161], v[170:173], v[50:65]
	v_exp_f32_e32 v158, v116
	v_exp_f32_e32 v159, v117
	s_nop 0
	v_cvt_pk_bf16_f32 v115, v158, v159
	v_mfma_f32_32x32x16_bf16 v[34:49], v[154:157], v[170:173], v[34:49]
	v_exp_f32_e32 v154, v118
	v_exp_f32_e32 v155, v119
	s_nop 0
	v_cvt_pk_bf16_f32 v116, v154, v155
	v_mfma_f32_32x32x16_bf16 v[18:33], v[150:153], v[170:173], v[18:33]
	v_exp_f32_e32 v150, v120
	v_exp_f32_e32 v151, v121
	v_add_f32_e32 v152, v162, v225
	v_add_f32_e32 v152, v163, v152
	v_add_f32_e32 v152, v158, v152
	v_cvt_pk_bf16_f32 v117, v150, v151
	v_add_f32_e32 v152, v159, v152
	s_waitcnt lgkmcnt(14)
	v_mfma_f32_32x32x16_bf16 v[66:81], v[166:169], v[174:177], v[66:81]
	v_exp_f32_e32 v122, v122
	v_exp_f32_e32 v123, v123
	v_add_f32_e32 v152, v154, v152
	v_add_f32_e32 v152, v155, v152
	v_add_f32_e32 v150, v150, v152
	v_cvt_pk_bf16_f32 v170, v122, v123
	v_add_f32_e32 v150, v151, v150
	s_waitcnt lgkmcnt(12)
	v_mfma_f32_32x32x16_bf16 v[50:65], v[178:181], v[174:177], v[50:65]
	v_exp_f32_e32 v124, v124
	v_exp_f32_e32 v125, v125
	v_add_f32_e32 v122, v122, v150
	v_add_f32_e32 v122, v123, v122
	v_add_f32_e32 v122, v124, v122
	v_cvt_pk_bf16_f32 v171, v124, v125
	v_add_f32_e32 v122, v125, v122
	s_waitcnt lgkmcnt(10)
	v_mfma_f32_32x32x16_bf16 v[34:49], v[182:185], v[174:177], v[34:49]
	v_exp_f32_e32 v126, v126
	v_exp_f32_e32 v127, v127
	v_add_f32_e32 v122, v126, v122
	v_cvt_pk_bf16_f32 v172, v126, v127
	v_add_f32_e32 v122, v127, v122
	s_waitcnt lgkmcnt(8)
	v_mfma_f32_32x32x16_bf16 v[18:33], v[226:229], v[174:177], v[18:33]
	v_exp_f32_e32 v128, v128
	v_exp_f32_e32 v129, v129
	v_add_f32_e32 v122, v128, v122
	v_cvt_pk_bf16_f32 v173, v128, v129
	v_add_f32_e32 v122, v129, v122
	v_mfma_f32_32x32x16_bf16 v[98:113], v[146:149], v[142:145], v[98:113]
	s_waitcnt lgkmcnt(0)
	v_mfma_f32_32x32x16_bf16 v[66:81], v[230:233], v[114:117], v[66:81]
	v_add_f32_e32 v209, v209, v122
	ds_read_b64_tr_b16 v[246:247], v210 offset:12288
	ds_read_b64_tr_b16 v[248:249], v210 offset:14336
	ds_read_b64_tr_b16 v[202:203], v211 offset:12288
	ds_read_b64_tr_b16 v[204:205], v211 offset:14336
	ds_read_b64_tr_b16 v[216:217], v224 offset:12288
	ds_read_b64_tr_b16 v[218:219], v224 offset:14336
	ds_read_b64_tr_b16 v[210:211], v223 offset:12288
	ds_read_b64_tr_b16 v[212:213], v223 offset:14336
	v_add_u32_e32 v122, s22, v201
	v_add_u32_e32 v123, s22, v206
	ds_read_b64_tr_b16 v[162:163], v122 offset:0
	ds_read_b64_tr_b16 v[164:165], v122 offset:2048
	ds_read_b64_tr_b16 v[158:159], v123 offset:0
	ds_read_b64_tr_b16 v[160:161], v123 offset:2048
	v_mfma_f32_32x32x16_bf16 v[50:65], v[234:237], v[114:117], v[50:65]
	v_exp_f32_e32 v226, v82
	v_exp_f32_e32 v227, v83
	v_exp_f32_e32 v228, v84
	v_mfma_f32_32x32x16_bf16 v[34:49], v[238:241], v[114:117], v[34:49]
	v_add_u32_e32 v223, s22, v207
	v_add_u32_e32 v224, s22, v208
	ds_read_b64_tr_b16 v[154:155], v223 offset:0
	ds_read_b64_tr_b16 v[156:157], v223 offset:2048
	ds_read_b64_tr_b16 v[150:151], v224 offset:0
	ds_read_b64_tr_b16 v[152:153], v224 offset:2048
	v_mfma_f32_32x32x16_bf16 v[18:33], v[242:245], v[114:117], v[18:33]
	v_exp_f32_e32 v229, v85
	v_exp_f32_e32 v230, v86
	v_exp_f32_e32 v231, v87
	s_setprio 0
	s_add_i32 s26, s22, 0x8000
	s_cmp_lg_u32 s22, 0x18000
	s_mov_b32 s25, s22
	s_cselect_b32 s22, s26, 0
	s_add_i32 s26, s23, 0x8000
	s_cmp_lg_u32 s23, 0x18000
	s_cselect_b32 s23, s26, 0
	s_add_i32 s24, s24, 1
	s_cmp_eq_u32 s24, 32
	s_cbranch_scc0 .LBB0_366
	s_waitcnt lgkmcnt(0)
	v_mfma_f32_32x32x16_bf16 v[66:81], v[246:249], v[170:173], v[66:81]
	v_mfma_f32_32x32x16_bf16 v[50:65], v[202:205], v[170:173], v[50:65]
	v_mfma_f32_32x32x16_bf16 v[34:49], v[210:213], v[170:173], v[34:49]
	v_mfma_f32_32x32x16_bf16 v[18:33], v[216:219], v[170:173], v[18:33]
	s_nop 15
	global_load_dwordx4 v[98:101], v0, s[10:11]
	global_load_dwordx4 v[102:105], v0, s[10:11] offset:32
	global_load_dwordx4 v[106:109], v0, s[10:11] offset:64
	global_load_dwordx4 v[110:113], v0, s[10:11] offset:96
	global_load_dwordx4 v[114:117], v0, s[10:11] offset:128
	global_load_dwordx4 v[118:121], v0, s[10:11] offset:160
	global_load_dwordx4 v[122:125], v0, s[10:11] offset:192
	global_load_dwordx4 v[126:129], v0, s[10:11] offset:224
	global_load_dwordx4 v[130:133], v0, s[10:11] offset:256
	global_load_dwordx4 v[134:137], v0, s[10:11] offset:288
	global_load_dwordx4 v[138:141], v0, s[10:11] offset:320
	global_load_dwordx4 v[142:145], v0, s[10:11] offset:352
	global_load_dwordx4 v[146:149], v0, s[10:11] offset:384
	global_load_dwordx4 v[150:153], v0, s[10:11] offset:416
	global_load_dwordx4 v[154:157], v0, s[10:11] offset:448
	global_load_dwordx4 v[158:161], v0, s[10:11] offset:480
	ds_bpermute_b32 v82, v221, v209
	s_lshl_b32 s17, s21, 14
	s_add_i32 s17, s17, 0
	s_waitcnt vmcnt(0)
	s_cmp_eq_u32 s16, 0
	s_waitcnt lgkmcnt(0)
	v_add_f32_e32 v82, v209, v82
	v_div_scale_f32 v83, s[22:23], v82, v82, 1.0
	v_rcp_f32_e32 v84, v83
	v_div_scale_f32 v85, vcc, 1.0, v82, 1.0
	v_lshl_add_u32 v92, v196, 4, s17
	v_fma_f32 v86, -v83, v84, 1.0
	v_fmac_f32_e32 v84, v86, v84
	v_mul_f32_e32 v86, v85, v84
	v_fma_f32 v87, -v83, v86, v85
	v_fmac_f32_e32 v86, v87, v84
	v_fma_f32 v83, -v83, v86, v85
	v_div_fmas_f32 v83, v83, v84, v86
	s_cselect_b64 s[16:17], -1, 0
	v_div_fixup_f32 v82, v83, v82, 1.0
	s_and_b64 vcc, exec, s[16:17]
	s_waitcnt vmcnt(0)
	s_barrier
	s_cbranch_vccnz .LBB0_369
	v_pk_mul_f32 v[86:87], v[68:69], v[82:83] op_sel_hi:[1,0]
	v_pk_mul_f32 v[84:85], v[66:67], v[82:83] op_sel_hi:[1,0]
	ds_write_b128 v92, v[84:87]
	v_pk_mul_f32 v[86:87], v[72:73], v[82:83] op_sel_hi:[1,0]
	v_pk_mul_f32 v[84:85], v[70:71], v[82:83] op_sel_hi:[1,0]
	ds_write_b128 v92, v[84:87] offset:1024
	v_pk_mul_f32 v[86:87], v[76:77], v[82:83] op_sel_hi:[1,0]
	v_pk_mul_f32 v[84:85], v[74:75], v[82:83] op_sel_hi:[1,0]
	ds_write_b128 v92, v[84:87] offset:2048
	v_pk_mul_f32 v[86:87], v[80:81], v[82:83] op_sel_hi:[1,0]
	v_pk_mul_f32 v[84:85], v[78:79], v[82:83] op_sel_hi:[1,0]
	ds_write_b128 v92, v[84:87] offset:3072
	v_pk_mul_f32 v[86:87], v[52:53], v[82:83] op_sel_hi:[1,0]
	v_pk_mul_f32 v[84:85], v[50:51], v[82:83] op_sel_hi:[1,0]
	ds_write_b128 v92, v[84:87] offset:4096
	v_pk_mul_f32 v[86:87], v[56:57], v[82:83] op_sel_hi:[1,0]
	v_pk_mul_f32 v[84:85], v[54:55], v[82:83] op_sel_hi:[1,0]
	ds_write_b128 v92, v[84:87] offset:5120
	v_pk_mul_f32 v[86:87], v[60:61], v[82:83] op_sel_hi:[1,0]
	v_pk_mul_f32 v[84:85], v[58:59], v[82:83] op_sel_hi:[1,0]
	ds_write_b128 v92, v[84:87] offset:6144
	v_pk_mul_f32 v[86:87], v[64:65], v[82:83] op_sel_hi:[1,0]
	v_pk_mul_f32 v[84:85], v[62:63], v[82:83] op_sel_hi:[1,0]
	ds_write_b128 v92, v[84:87] offset:7168
	v_pk_mul_f32 v[86:87], v[36:37], v[82:83] op_sel_hi:[1,0]
	v_pk_mul_f32 v[84:85], v[34:35], v[82:83] op_sel_hi:[1,0]
	ds_write_b128 v92, v[84:87] offset:8192
	v_pk_mul_f32 v[86:87], v[40:41], v[82:83] op_sel_hi:[1,0]
	v_pk_mul_f32 v[84:85], v[38:39], v[82:83] op_sel_hi:[1,0]
	ds_write_b128 v92, v[84:87] offset:9216
	v_pk_mul_f32 v[86:87], v[44:45], v[82:83] op_sel_hi:[1,0]
	v_pk_mul_f32 v[84:85], v[42:43], v[82:83] op_sel_hi:[1,0]
	ds_write_b128 v92, v[84:87] offset:10240
	v_pk_mul_f32 v[86:87], v[48:49], v[82:83] op_sel_hi:[1,0]
	v_pk_mul_f32 v[84:85], v[46:47], v[82:83] op_sel_hi:[1,0]
	ds_write_b128 v92, v[84:87] offset:11264
	v_pk_mul_f32 v[86:87], v[20:21], v[82:83] op_sel_hi:[1,0]
	v_pk_mul_f32 v[84:85], v[18:19], v[82:83] op_sel_hi:[1,0]
	ds_write_b128 v92, v[84:87] offset:12288
	v_pk_mul_f32 v[86:87], v[24:25], v[82:83] op_sel_hi:[1,0]
	v_pk_mul_f32 v[84:85], v[22:23], v[82:83] op_sel_hi:[1,0]
	ds_write_b128 v92, v[84:87] offset:13312
	v_pk_mul_f32 v[86:87], v[28:29], v[82:83] op_sel_hi:[1,0]
	v_pk_mul_f32 v[84:85], v[26:27], v[82:83] op_sel_hi:[1,0]
	ds_write_b128 v92, v[84:87] offset:14336
	v_pk_mul_f32 v[86:87], v[32:33], v[82:83] op_sel_hi:[1,0]
	v_pk_mul_f32 v[84:85], v[30:31], v[82:83] op_sel_hi:[1,0]
	ds_write_b128 v92, v[84:87] offset:15360
